# GQA loop: fast path with softmax reference 0 (no per-element subtraction), tile-sum overflow/underflow guards fall back to the running-max loop
# speedup vs baseline: 1.0219x; 1.0219x over previous
; DI int opaque_tid() { int t = threadIdx.x; asm volatile("" : "+v"(t)); return t; }
; DI void flash_pass_q2(f32x16 (&o)[2][2], const u16* __restrict__ Qp0, const u16* __restrict__ Qp1,
;                       const u16* __restrict__ Kb, int ldk, const u16* __restrict__ Vt, int S, int ntiles, char* lds) {
;   const int tid = opaque_tid(), lane = tid & 63;
;   const int h = lane >> 5, r = lane & 31;
;   bf16x8 q[2][4];
; #pragma unroll
;   for (int ks = 0; ks < 4; ++ks) {
;     q[0][ks] = *(const bf16x8*)(Qp0 + ks * 16 + h * 8);
;     q[1][ks] = *(const bf16x8*)(Qp1 + ks * 16 + h * 8);
;   }
; #pragma unroll
;   for (int hq = 0; hq < 2; ++hq)
; #pragma unroll
;     for (int mv = 0; mv < 2; ++mv)
; #pragma unroll
;       for (int i = 0; i < 16; ++i) o[hq][mv][i] = 0.f;
;   float m_run[2] = {-INFINITY, -INFINITY}, l_run[2] = {0.f, 0.f};
;   const int lr = tid >> 3, lc = tid & 7;
;   const int wsw = lr * 128 + ((lc ^ ((lr >> 1) & 7)) << 4);
;   u32x4 rk, rv;
;   auto gload = [&](int ti) {
;     const size_t key0 = (size_t)ti * 64;
;     rk = *(const u32x4*)(Kb + (key0 + lr) * ldk + lc * 8);
;     rv = *(const u32x4*)(Vt + (size_t)lr * S + key0 + lc * 8);
;   };
;   auto swrite = [&](int st) {
;     char* ks_ = lds + st * ATT_STAGE;
;     *(u32x4*)(ks_ + wsw) = rk;
;     *(u32x4*)(ks_ + 8192 + wsw) = rv;
;   };
;   const int pr = (r & 0x13) | ((r & 4) << 1) | ((r & 8) >> 1);
;   const int ksw = (pr >> 1) & 7;
;   const int vsw = (r >> 1) & 7;
;   __syncthreads();
;   gload(0);
;   swrite(0);
;   if (ntiles > 1) gload(1);
;   __syncthreads();
; DI void phase_attn0(const Params& p, char* lds) {
;     ...
;     if (lt < 512) { cls = 0; bb = lt >> 8; head = (lt >> 6) & 3; qb = lt & 63; }
;     else if (lt < 1024) { int u = lt - 512; cls = 1; bb = u >> 8; head = (u >> 6) & 3; qb = u & 63; }
;     else if (lt < 1280) { int u = lt - 1024; cls = 0; bb = 2 + (u >> 5); head = (u >> 3) & 3; qb = u & 7; }
;     else { int u = lt - 1280; cls = 1; bb = 2 + (u >> 5); head = (u >> 3) & 3; qb = u & 7; }
;     if (bb < 2) { S = SP; tokbase = bb * SP; } else { S = SS; tokbase = NTOK_P + (bb - 2) * SS; }
;     const int tq = tokbase + qb * 256 + w * 32 + r;
;     const u16* Kseq = QK + (size_t)tokbase * QK0_LD;
;     const u16* Vseq = VT + (size_t)640 * tokbase;
.LBB0_275:
	s_andn2_saveexec_b64 s[18:19], s[18:19]
	v_ashrrev_i32_e32 v2, 8, v0
	v_lshrrev_b32_e32 v8, 6, v0
	v_and_b32_e32 v3, 63, v0
	s_or_b64 s[16:17], s[16:17], exec
	s_or_b64 exec, exec, s[18:19]
	v_lshlrev_b32_e32 v0, 14, v2
	v_lshl_add_u32 v4, v2, 11, v220
	v_cmp_gt_i32_e32 vcc, 2, v2
	v_lshlrev_b32_e32 v2, 8, v3
	v_mov_b64_e32 v[10:11], s[2:3]
	v_cndmask_b32_e32 v0, v4, v0, vcc
	s_movk_i32 s20, 0x500
	v_add3_u32 v196, v226, v2, v0
	v_mad_i64_i32 v[2:3], s[18:19], v0, s96, 0
	v_mad_i64_i32 v[160:161], s[18:19], v0, s96, v[10:11]
	v_mad_i64_i32 v[4:5], s[18:19], v0, s20, 0
	v_readlane_b32 s18, v254, 1
	v_readlane_b32 s19, v254, 2
	v_and_b32_e32 v9, 3, v8
	v_cndmask_b32_e32 v12, v221, v222, vcc
	v_mov_b64_e32 v[6:7], s[18:19]
	s_xor_b64 s[16:17], s[16:17], -1
	v_mad_i64_i32 v[6:7], s[18:19], v0, s20, v[6:7]
	v_ashrrev_i32_e32 v197, 31, v196
	v_mad_i64_i32 v[162:163], s[18:19], v196, s96, v[10:11]
	v_lshlrev_b32_e32 v198, 7, v9
	v_lshrrev_b32_e32 v185, 6, v12
	s_waitcnt vmcnt(9)
	v_cndmask_b32_e64 v176, 11, 14, vcc
	s_and_saveexec_b64 s[18:19], s[16:17]
	s_xor_b64 s[16:17], exec, s[18:19]
	s_cbranch_execz .LBB0_291
	v_lshlrev_b32_e32 v0, 8, v9
	v_lshl_add_u64 v[10:11], v[162:163], 0, v[0:1]
	v_lshlrev_b32_e32 v0, 5, v9
	v_and_b32_e32 v9, 64, v0
	v_lshlrev_b32_e32 v0, 1, v9
	v_lshl_add_u64 v[12:13], v[160:161], 0, v[0:1]
	v_or_b32_e32 v0, 0x200, v9
	v_mov_b32_e32 v9, v204
	v_mov_b32_e32 v15, v1
	v_bfe_u32 v24, v9, 5, 1
	v_lshlrev_b32_e32 v14, 4, v24
	v_lshl_add_u64 v[10:11], v[10:11], 0, v[14:15]
	v_ashrrev_i32_e32 v18, 3, v9
	v_lshlrev_b32_e32 v25, 4, v9
	v_lshlrev_b32_e32 v0, v176, v0
	global_load_dwordx4 v[168:171], v[10:11], off offset:2048
	global_load_dwordx4 v[164:167], v[10:11], off offset:2080
	global_load_dwordx4 v[172:175], v[10:11], off offset:2176
	global_load_dwordx4 v[160:163], v[10:11], off offset:2208
	global_load_dwordx4 v[156:159], v[10:11], off offset:2112
	global_load_dwordx4 v[148:151], v[10:11], off offset:2144
	global_load_dwordx4 v[152:155], v[10:11], off offset:2240
	global_load_dwordx4 v[144:147], v[10:11], off offset:2272
	v_ashrrev_i32_e32 v19, 31, v18
	v_mad_i64_i32 v[10:11], s[18:19], v18, s96, v[12:13]
	v_and_b32_e32 v12, 0x70, v25
	v_mov_b32_e32 v13, v1
	v_lshlrev_b32_e32 v0, 1, v0
	v_lshl_add_u64 v[20:21], v[10:11], 0, v[12:13]
	v_lshlrev_b64 v[10:11], v176, v[18:19]
	v_lshl_add_u64 v[6:7], v[6:7], 0, v[0:1]
	v_lshlrev_b64 v[22:23], 1, v[10:11]
	v_lshl_add_u64 v[6:7], v[6:7], 0, v[22:23]
	s_barrier
	v_lshl_add_u64 v[6:7], v[6:7], 0, v[12:13]
	global_load_dwordx4 v[10:13], v[20:21], off offset:3072
	global_load_dwordx4 v[14:17], v[6:7], off
	v_add_co_u32_e32 v20, vcc, s97, v20
	v_lshlrev_b32_e32 v19, 1, v9
	s_nop 0
	v_addc_co_u32_e32 v21, vcc, 0, v21, vcc
	global_load_dwordx4 v[176:179], v[20:21], off offset:3072
	global_load_dwordx4 v[180:183], v[6:7], off offset:128
	v_lshrrev_b32_e32 v20, 1, v9
	v_and_b32_e32 v7, 19, v9
	v_and_b32_e32 v19, 8, v19
	v_and_b32_e32 v20, 4, v20
	v_lshrrev_b32_e32 v6, 5, v9
	v_bfe_u32 v21, v9, 1, 3
	v_lshlrev_b32_e32 v26, 7, v9
	v_and_b32_e32 v27, 7, v9
	v_lshlrev_b32_e32 v28, 7, v18
	v_xor_b32_e32 v9, v25, v9
	v_or3_b32 v7, v19, v7, v20
	v_and_or_b32 v237, v9, s66, v28
	v_lshrrev_b32_e32 v9, 1, v7
	v_lshlrev_b32_e32 v238, 7, v7
	v_bitop3_b32 v7, v9, v24, 7 bitop3:0x6c
	v_bitop3_b32 v30, v6, v21, 1 bitop3:0x6c
	v_lshlrev_b32_e32 v6, 4, v27
	v_lshlrev_b32_e32 v239, 4, v7
	v_mov_b32_e32 v7, v1
	v_lshl_add_u64 v[4:5], v[4:5], 0, v[6:7]
	v_lshl_add_u64 v[4:5], v[4:5], 0, v[22:23]
	v_readlane_b32 s18, v254, 45
	v_lshl_add_u64 v[4:5], v[4:5], 0, v[0:1]
	v_readlane_b32 s19, v254, 46
	v_and_b32_e32 v0, 2, v8
	v_lshlrev_b32_e32 v0, 6, v0
	v_lshl_add_u64 v[200:201], s[18:19], 0, v[4:5]
	v_mad_i64_i32 v[2:3], s[18:19], v18, s96, v[2:3]
	v_and_b32_e32 v195, 0xf80, v26
	v_or_b32_e32 v25, 2, v24
	v_or_b32_e32 v26, 4, v24
	v_or_b32_e32 v29, 6, v24
	v_lshl_add_u64 v[2:3], v[2:3], 0, v[0:1]
	v_readlane_b32 s18, v254, 47
	v_bitop3_b32 v31, v24, v21, 2 bitop3:0x36
	v_bitop3_b32 v32, v24, v21, 4 bitop3:0x36
	v_bitop3_b32 v21, v24, v21, 6 bitop3:0x36
	v_bitop3_b32 v19, v9, v25, 7 bitop3:0x6c
	v_bitop3_b32 v20, v9, v26, 7 bitop3:0x6c
	v_bitop3_b32 v9, v9, v29, 7 bitop3:0x6c
	v_lshl_add_u64 v[2:3], v[2:3], 0, v[6:7]
	v_readlane_b32 s19, v254, 48
	v_lshlrev_b32_e32 v232, 4, v30
	v_lshlrev_b32_e32 v231, 4, v31
	v_lshlrev_b32_e32 v230, 4, v32
	v_lshlrev_b32_e32 v228, 4, v21
	v_lshlrev_b32_e32 v236, 4, v19
	v_lshlrev_b32_e32 v235, 4, v20
	v_lshlrev_b32_e32 v234, 4, v9
	v_lshl_add_u64 v[202:203], s[18:19], 0, v[2:3]
	v_mov_b32_e32 v0, v1
	v_mov_b32_e32 v2, v1
	s_waitcnt vmcnt(3)
	ds_write_b128 v237, v[10:13]
	s_waitcnt vmcnt(2)
	ds_write_b128 v237, v[14:17] offset:8192
	v_mov_b32_e32 v14, v1
	v_mov_b32_e32 v15, v1
	v_mov_b32_e32 v3, v1
	v_mov_b32_e32 v4, v1
	v_mov_b32_e32 v5, v1
	v_mov_b32_e32 v6, v1
	v_mov_b32_e32 v8, v1
	v_mov_b32_e32 v9, v1
	v_mov_b32_e32 v10, v1
	v_mov_b32_e32 v11, v1
	v_mov_b32_e32 v12, v1
	v_mov_b32_e32 v13, v1
	v_mov_b64_e32 v[30:31], v[14:15]
	v_mov_b64_e32 v[46:47], v[14:15]
	v_mov_b64_e32 v[62:63], v[14:15]
	v_mov_b64_e32 v[78:79], v[14:15]
	s_mov_b32 s22, 1
	v_mov_b32_e32 v229, 0
	v_mov_b32_e32 v233, 0xff800000
	s_mov_b64 s[18:19], 0
	v_mov_b64_e32 v[28:29], v[12:13]
	v_mov_b64_e32 v[26:27], v[10:11]
	v_mov_b64_e32 v[24:25], v[8:9]
	v_mov_b64_e32 v[22:23], v[6:7]
	v_mov_b64_e32 v[20:21], v[4:5]
	v_mov_b64_e32 v[18:19], v[2:3]
	v_mov_b64_e32 v[16:17], v[0:1]
	v_mov_b64_e32 v[44:45], v[12:13]
	v_mov_b64_e32 v[42:43], v[10:11]
	v_mov_b64_e32 v[40:41], v[8:9]
	v_mov_b64_e32 v[38:39], v[6:7]
	v_mov_b64_e32 v[36:37], v[4:5]
	v_mov_b64_e32 v[34:35], v[2:3]
	v_mov_b64_e32 v[32:33], v[0:1]
	v_mov_b64_e32 v[60:61], v[12:13]
	v_mov_b64_e32 v[58:59], v[10:11]
	v_mov_b64_e32 v[56:57], v[8:9]
	v_mov_b64_e32 v[54:55], v[6:7]
	v_mov_b64_e32 v[52:53], v[4:5]
	v_mov_b64_e32 v[50:51], v[2:3]
	v_mov_b64_e32 v[48:49], v[0:1]
	v_mov_b64_e32 v[76:77], v[12:13]
	v_mov_b64_e32 v[74:75], v[10:11]
	v_mov_b64_e32 v[72:73], v[8:9]
	v_mov_b64_e32 v[70:71], v[6:7]
	v_mov_b64_e32 v[68:69], v[4:5]
	v_mov_b64_e32 v[66:67], v[2:3]
	v_mov_b64_e32 v[64:65], v[0:1]
	v_mov_b32_e32 v10, 0xff800000
	v_mov_b32_e32 v0, 0
	s_waitcnt lgkmcnt(0)
	s_barrier
	v_mov_b32_e32 v10, 0
	v_mov_b32_e32 v233, 0
	s_mov_b32 s100, 0x2b800000
	s_branch .LBB0_280

; #define MFMA(a, b, c) __builtin_amdgcn_mfma_f32_32x32x16_bf16((a), (b), (c), 0, 0, 0)
; DI float fexp2(float x) { return __builtin_amdgcn_exp2f(x); }
; DI void flash_pass_q2(f32x16 (&o)[2][2], const u16* __restrict__ Qp0, const u16* __restrict__ Qp1,
;                       const u16* __restrict__ Kb, int ldk, const u16* __restrict__ Vt, int S, int ntiles, char* lds) {
;     ...
;     {
;       bf16x8 ka[4], kb_[4];
; #pragma unroll
;       for (int ks = 0; ks < 4; ++ks) {
;         const int co = ((2 * ks + h) ^ ksw) << 4;
;         ka[ks] = *(const bf16x8*)(st + pr * 128 + co);
;         kb_[ks] = *(const bf16x8*)(st + (32 + pr) * 128 + co);
;       }
;       asm volatile("" ::: "memory");
; #pragma unroll
;       for (int ks = 0; ks < 4; ++ks) {
;         s[0][0] = MFMA(ka[ks], q[0][ks], s[0][0]);
;         s[0][1] = MFMA(kb_[ks], q[0][ks], s[0][1]);
;         s[1][0] = MFMA(ka[ks], q[1][ks], s[1][0]);
;         s[1][1] = MFMA(kb_[ks], q[1][ks], s[1][1]);
;       }
;     }
;     bf16x8 pf[2][2][2];
; #pragma unroll
;     for (int hq = 0; hq < 2; ++hq) {
;       float t[32];
; #pragma unroll
;       for (int i = 0; i < 16; ++i) { t[i] = s[hq][0][i]; t[16 + i] = s[hq][1][i]; }
;       float mx = t[0];
; #pragma unroll
;       for (int e = 1; e < 32; ++e) mx = fmaxf(mx, t[e]);
;       mx = fmaxf(mx, __shfl_xor(mx, 32));
;       if (__builtin_amdgcn_ballot_w64(mx > m_run[hq] + 8.f) != 0ull) {
;         const float m_new = fmaxf(m_run[hq], mx);
;         const float alpha = fexp2(m_run[hq] - m_new);
;         l_run[hq] *= alpha;
;         m_run[hq] = m_new;
; #pragma unroll
;         for (int mv = 0; mv < 2; ++mv)
; #pragma unroll
;           for (int i = 0; i < 16; ++i) o[hq][mv][i] *= alpha;
;       }
;       float ls = 0.f;
; #pragma unroll
;       for (int e = 0; e < 32; ++e) { t[e] = fexp2(t[e] - m_run[hq]); ls += t[e]; }
;       l_run[hq] += ls;
.Lg2_noloadf:
	s_or_b64 exec, exec, s[20:21]
	v_cmp_eq_u32_e32 vcc, s22, v185
	s_waitcnt lgkmcnt(5)
	v_mfma_f32_32x32x16_bf16 v[128:143], v[2:5], v[168:171], 0
	s_waitcnt lgkmcnt(4)
	v_mfma_f32_32x32x16_bf16 v[112:127], v[6:9], v[168:171], 0
	v_mfma_f32_32x32x16_bf16 v[96:111], v[2:5], v[172:175], 0
	v_mfma_f32_32x32x16_bf16 v[80:95], v[6:9], v[172:175], 0
	s_or_b64 s[18:19], vcc, s[18:19]
	v_add_u32_e32 v249, v11, v235
	ds_read_b128 v[2:5], v249
	ds_read_b128 v[6:9], v249 offset:4096
	s_waitcnt lgkmcnt(5)
	v_mfma_f32_32x32x16_bf16 v[128:143], v[12:15], v[164:167], v[128:143]
	s_waitcnt lgkmcnt(4)
	v_mfma_f32_32x32x16_bf16 v[112:127], v[240:243], v[164:167], v[112:127]
	v_mfma_f32_32x32x16_bf16 v[96:111], v[12:15], v[160:163], v[96:111]
	v_mfma_f32_32x32x16_bf16 v[80:95], v[240:243], v[160:163], v[80:95]
	v_add_u32_e32 v249, v11, v234
	ds_read_b128 v[12:15], v249
	ds_read_b128 v[240:243], v249 offset:4096
	s_waitcnt lgkmcnt(3)
	v_mfma_f32_32x32x16_bf16 v[128:143], v[2:5], v[156:159], v[128:143]
	s_waitcnt lgkmcnt(2)
	v_mfma_f32_32x32x16_bf16 v[112:127], v[6:9], v[156:159], v[112:127]
	v_mfma_f32_32x32x16_bf16 v[96:111], v[2:5], v[152:155], v[96:111]
	v_mfma_f32_32x32x16_bf16 v[80:95], v[6:9], v[152:155], v[80:95]
	v_add_u32_e32 v249, v248, v232
	ds_read_b128 v[2:5], v249 offset:8192
	ds_read_b128 v[6:9], v249 offset:12288
	s_waitcnt lgkmcnt(3)
	v_mfma_f32_32x32x16_bf16 v[128:143], v[12:15], v[148:151], v[128:143]
	s_waitcnt lgkmcnt(2)
	v_mfma_f32_32x32x16_bf16 v[112:127], v[240:243], v[148:151], v[112:127]
	v_mfma_f32_32x32x16_bf16 v[96:111], v[12:15], v[144:147], v[96:111]
	v_mfma_f32_32x32x16_bf16 v[80:95], v[240:243], v[144:147], v[80:95]
	v_add_u32_e32 v249, v248, v231
	ds_read_b128 v[12:15], v249 offset:8192
	ds_read_b128 v[240:243], v249 offset:12288
	s_nop 4
	v_exp_f32_e32 v128, v128
	v_exp_f32_e32 v129, v129
	v_exp_f32_e32 v130, v130
	v_exp_f32_e32 v131, v131
	v_exp_f32_e32 v132, v132
	v_exp_f32_e32 v133, v133
	v_exp_f32_e32 v134, v134
	v_exp_f32_e32 v135, v135
	v_exp_f32_e32 v136, v136
	v_exp_f32_e32 v137, v137
	v_add_f32_e32 v210, v128, v130
	v_add_f32_e32 v246, v129, v131
	v_exp_f32_e32 v138, v138
	v_exp_f32_e32 v139, v139
	v_add_f32_e32 v210, v210, v132
	v_add_f32_e32 v246, v246, v133
	v_exp_f32_e32 v140, v140
	v_exp_f32_e32 v141, v141
	v_add_f32_e32 v210, v210, v134
	v_add_f32_e32 v246, v246, v135
	v_exp_f32_e32 v142, v142
	v_exp_f32_e32 v143, v143
	v_add_f32_e32 v210, v210, v136
	v_add_f32_e32 v246, v246, v137
	v_exp_f32_e32 v112, v112
	v_exp_f32_e32 v113, v113
	v_add_f32_e32 v210, v210, v138
	v_add_f32_e32 v246, v246, v139
	v_exp_f32_e32 v114, v114
	v_exp_f32_e32 v115, v115
	v_add_f32_e32 v210, v210, v140
	v_add_f32_e32 v246, v246, v141
	v_exp_f32_e32 v116, v116
	v_exp_f32_e32 v117, v117
	v_add_f32_e32 v210, v210, v142
	v_add_f32_e32 v246, v246, v143
	v_exp_f32_e32 v118, v118
	v_exp_f32_e32 v119, v119
	v_add_f32_e32 v210, v210, v112
	v_add_f32_e32 v246, v246, v113
	v_exp_f32_e32 v120, v120
	v_exp_f32_e32 v121, v121
	v_add_f32_e32 v210, v210, v114
	v_add_f32_e32 v246, v246, v115
	v_exp_f32_e32 v122, v122
	v_exp_f32_e32 v123, v123
	v_add_f32_e32 v210, v210, v116
	v_add_f32_e32 v246, v246, v117
	v_exp_f32_e32 v124, v124
	v_exp_f32_e32 v125, v125
	v_add_f32_e32 v210, v210, v118
	v_add_f32_e32 v246, v246, v119
	v_exp_f32_e32 v126, v126
	v_exp_f32_e32 v127, v127
	v_add_f32_e32 v210, v210, v120
	v_add_f32_e32 v246, v246, v121
	v_add_f32_e32 v210, v210, v122
	v_add_f32_e32 v246, v246, v123
	v_add_f32_e32 v210, v210, v124
	v_add_f32_e32 v246, v246, v125
	v_add_f32_e32 v210, v210, v126
	v_add_f32_e32 v246, v246, v127
	v_add_f32_e32 v210, v210, v246
	v_cmp_lt_f32_e32 vcc, 0x5d800000, v210
	s_cbranch_vccnz .Lg3_ovf0
	v_cmp_gt_f32_e32 vcc, s100, v210
	s_cbranch_vccnz .Lg3_unf0
; #define MFMA(a, b, c) __builtin_amdgcn_mfma_f32_32x32x16_bf16((a), (b), (c), 0, 0, 0)
; DI float fexp2(float x) { return __builtin_amdgcn_exp2f(x); }
; DI void flash_pass_q2(f32x16 (&o)[2][2], const u16* __restrict__ Qp0, const u16* __restrict__ Qp1,
;                       const u16* __restrict__ Kb, int ldk, const u16* __restrict__ Vt, int S, int ntiles, char* lds) {
;     ...
;       float ls = 0.f;
; #pragma unroll
;       for (int e = 0; e < 32; ++e) { t[e] = fexp2(t[e] - m_run[hq]); ls += t[e]; }
;       l_run[hq] += ls;
; #pragma unroll
;       for (int kb = 0; kb < 2; ++kb)
; #pragma unroll
;         for (int c2 = 0; c2 < 2; ++c2) {
;           const int e0 = kb * 16 + c2 * 8;
;           u32x4 pw = {pk_bf16(t[e0], t[e0 + 1]), pk_bf16(t[e0 + 2], t[e0 + 3]), pk_bf16(t[e0 + 4], t[e0 + 5]), pk_bf16(t[e0 + 6], t[e0 + 7])};
;           pf[hq][kb][c2] = __builtin_bit_cast(bf16x8, pw);
;         }
;     }
;     bf16x8 vf[2][2][2];
; #pragma unroll
;     for (int kb = 0; kb < 2; ++kb)
; #pragma unroll
;       for (int c2 = 0; c2 < 2; ++c2) {
;         const int co = ((4 * kb + 2 * c2 + h) ^ vsw) << 4;
; #pragma unroll
;         for (int mv = 0; mv < 2; ++mv) vf[kb][c2][mv] = *(const bf16x8*)(st + 8192 + (mv * 32 + r) * 128 + co);
;       }
;     asm volatile("" ::: "memory");
; #pragma unroll
;     for (int kb = 0; kb < 2; ++kb)
; #pragma unroll
;       for (int c2 = 0; c2 < 2; ++c2)
; #pragma unroll
;         for (int mv = 0; mv < 2; ++mv) {
;           o[0][mv] = MFMA(vf[kb][c2][mv], pf[0][kb][c2], o[0][mv]);
;           o[1][mv] = MFMA(vf[kb][c2][mv], pf[1][kb][c2], o[1][mv]);
;         }
;     __syncthreads();
	v_add_f32_e32 v0, v0, v210
	v_cvt_pk_bf16_f32 v128, v128, v129
	v_cvt_pk_bf16_f32 v129, v130, v131
	v_cvt_pk_bf16_f32 v130, v132, v133
	v_cvt_pk_bf16_f32 v131, v134, v135
	v_cvt_pk_bf16_f32 v136, v136, v137
	v_cvt_pk_bf16_f32 v137, v138, v139
	v_cvt_pk_bf16_f32 v138, v140, v141
	v_cvt_pk_bf16_f32 v139, v142, v143
	v_cvt_pk_bf16_f32 v112, v112, v113
	v_cvt_pk_bf16_f32 v113, v114, v115
	v_cvt_pk_bf16_f32 v114, v116, v117
	v_cvt_pk_bf16_f32 v115, v118, v119
	v_cvt_pk_bf16_f32 v120, v120, v121
	v_cvt_pk_bf16_f32 v121, v122, v123
	v_cvt_pk_bf16_f32 v122, v124, v125
	v_cvt_pk_bf16_f32 v123, v126, v127
	s_waitcnt lgkmcnt(3)
	v_mfma_f32_32x32x16_bf16 v[64:79], v[2:5], v[128:131], v[64:79]
	s_waitcnt lgkmcnt(2)
	v_mfma_f32_32x32x16_bf16 v[48:63], v[6:9], v[128:131], v[48:63]
	s_waitcnt lgkmcnt(1)
	v_mfma_f32_32x32x16_bf16 v[64:79], v[12:15], v[136:139], v[64:79]
	s_waitcnt lgkmcnt(0)
	v_mfma_f32_32x32x16_bf16 v[48:63], v[240:243], v[136:139], v[48:63]
	v_exp_f32_e32 v96, v96
	v_exp_f32_e32 v97, v97
	v_exp_f32_e32 v98, v98
	v_exp_f32_e32 v99, v99
	v_exp_f32_e32 v100, v100
	v_exp_f32_e32 v101, v101
	v_exp_f32_e32 v102, v102
	v_exp_f32_e32 v103, v103
	v_exp_f32_e32 v104, v104
	v_exp_f32_e32 v105, v105
	v_add_f32_e32 v210, v96, v98
	v_add_f32_e32 v246, v97, v99
	v_exp_f32_e32 v106, v106
	v_exp_f32_e32 v107, v107
	v_add_f32_e32 v210, v210, v100
	v_add_f32_e32 v246, v246, v101
	v_exp_f32_e32 v108, v108
	v_exp_f32_e32 v109, v109
	v_add_f32_e32 v210, v210, v102
	v_add_f32_e32 v246, v246, v103
	v_exp_f32_e32 v110, v110
	v_exp_f32_e32 v111, v111
	v_add_f32_e32 v210, v210, v104
	v_add_f32_e32 v246, v246, v105
	v_exp_f32_e32 v80, v80
	v_exp_f32_e32 v81, v81
	v_add_f32_e32 v210, v210, v106
	v_add_f32_e32 v246, v246, v107
	v_exp_f32_e32 v82, v82
	v_exp_f32_e32 v83, v83
	v_add_f32_e32 v210, v210, v108
	v_add_f32_e32 v246, v246, v109
	v_exp_f32_e32 v84, v84
	v_exp_f32_e32 v85, v85
	v_add_f32_e32 v210, v210, v110
	v_add_f32_e32 v246, v246, v111
	v_exp_f32_e32 v86, v86
	v_exp_f32_e32 v87, v87
	v_add_f32_e32 v210, v210, v80
	v_add_f32_e32 v246, v246, v81
	v_exp_f32_e32 v88, v88
	v_exp_f32_e32 v89, v89
	v_add_f32_e32 v210, v210, v82
	v_add_f32_e32 v246, v246, v83
	v_exp_f32_e32 v90, v90
	v_exp_f32_e32 v91, v91
	v_add_f32_e32 v210, v210, v84
	v_add_f32_e32 v246, v246, v85
	v_exp_f32_e32 v92, v92
	v_exp_f32_e32 v93, v93
	v_add_f32_e32 v210, v210, v86
	v_add_f32_e32 v246, v246, v87
	v_exp_f32_e32 v94, v94
	v_exp_f32_e32 v95, v95
	v_add_f32_e32 v210, v210, v88
	v_add_f32_e32 v246, v246, v89
	v_add_f32_e32 v210, v210, v90
	v_add_f32_e32 v246, v246, v91
	v_add_f32_e32 v210, v210, v92
	v_add_f32_e32 v246, v246, v93
	v_add_f32_e32 v210, v210, v94
	v_add_f32_e32 v246, v246, v95
	v_add_f32_e32 v210, v210, v246
	v_cmp_lt_f32_e32 vcc, 0x5d800000, v210
	s_cbranch_vccnz .Lg3_ovf1
	v_cmp_gt_f32_e32 vcc, s100, v210
	s_cbranch_vccnz .Lg3_unf1
	v_add_f32_e32 v229, v229, v210
	v_cvt_pk_bf16_f32 v96, v96, v97
	v_cvt_pk_bf16_f32 v97, v98, v99
	v_cvt_pk_bf16_f32 v98, v100, v101
	v_cvt_pk_bf16_f32 v99, v102, v103
	v_cvt_pk_bf16_f32 v104, v104, v105
	v_cvt_pk_bf16_f32 v105, v106, v107
	v_cvt_pk_bf16_f32 v106, v108, v109
	v_cvt_pk_bf16_f32 v107, v110, v111
	v_cvt_pk_bf16_f32 v80, v80, v81
	v_cvt_pk_bf16_f32 v81, v82, v83
	v_cvt_pk_bf16_f32 v82, v84, v85
	v_cvt_pk_bf16_f32 v83, v86, v87
	v_cvt_pk_bf16_f32 v88, v88, v89
	v_cvt_pk_bf16_f32 v89, v90, v91
	v_cvt_pk_bf16_f32 v90, v92, v93
	v_cvt_pk_bf16_f32 v91, v94, v95
	v_mfma_f32_32x32x16_bf16 v[32:47], v[2:5], v[96:99], v[32:47]
	v_mfma_f32_32x32x16_bf16 v[16:31], v[6:9], v[96:99], v[16:31]
	v_add_u32_e32 v249, v248, v230
	ds_read_b128 v[2:5], v249 offset:8192
	ds_read_b128 v[6:9], v249 offset:12288
	v_mfma_f32_32x32x16_bf16 v[32:47], v[12:15], v[104:107], v[32:47]
	v_mfma_f32_32x32x16_bf16 v[16:31], v[240:243], v[104:107], v[16:31]
	v_add_u32_e32 v249, v248, v228
	ds_read_b128 v[12:15], v249 offset:8192
	ds_read_b128 v[240:243], v249 offset:12288
	s_waitcnt lgkmcnt(3)
	v_mfma_f32_32x32x16_bf16 v[64:79], v[2:5], v[112:115], v[64:79]
	s_waitcnt lgkmcnt(2)
	v_mfma_f32_32x32x16_bf16 v[48:63], v[6:9], v[112:115], v[48:63]
	v_mfma_f32_32x32x16_bf16 v[32:47], v[2:5], v[80:83], v[32:47]
	v_mfma_f32_32x32x16_bf16 v[16:31], v[6:9], v[80:83], v[16:31]
	s_waitcnt lgkmcnt(1)
	v_mfma_f32_32x32x16_bf16 v[64:79], v[12:15], v[120:123], v[64:79]
	s_waitcnt lgkmcnt(0)
	v_mfma_f32_32x32x16_bf16 v[48:63], v[240:243], v[120:123], v[48:63]
	v_mfma_f32_32x32x16_bf16 v[32:47], v[12:15], v[88:91], v[32:47]
	v_mfma_f32_32x32x16_bf16 v[16:31], v[240:243], v[88:91], v[16:31]
	v_mov_b32_e32 v14, s23
	s_waitcnt lgkmcnt(0)
	s_barrier
	s_andn2_b64 exec, exec, s[18:19]
	s_mov_b32 s100, 0
	s_cbranch_execnz .LBB0_280
	s_branch .LBB0_286
.Lg3_unf0:
	v_mov_b32_e32 v10, 0xff800000
.Lg3_ovf0:
	s_branch .Lg2_fix0
.Lg3_unf1:
	v_mov_b32_e32 v233, 0xff800000
